# move w_gate[0:10/16] bf16 conversion of both layers out of the P0 prologue into the idle waves (1-7) of four grid barriers
# speedup vs baseline: 1.0453x; 1.0053x over previous
;     ...
;     for (int mi = 0; mi < 7 * DEPTH; ++mi) {
;         if (!((mask >> mi) & 1u)) continue;
;         const int l = mi / 7, kind = mi - 7 * l;
;         const float* W; const float* ks = nullptr; bf16_t* WT; int K, N, rm = 0;
; __global__ void __launch_bounds__(NTHREADS, 2) mk_fwd(Args args) {
;     ...
;     if (KON(0) && IN(0)) { const int vcu = (G % 8 == 0) ? (blk % 8) * (G / 8) + blk / 8 : blk; p0_prologue(args, vcu * NWAVES + wave, G * NWAVES, lane, 0x000Fu | 0x0010u | 0x0800u, true, 0x0810u, 0, 10); }
.LBB0_11:
	s_lshl_b32 s48, 1, s43
	s_and_b32 s4, s48, 0xf
	s_cmp_eq_u32 s4, 0
	s_cbranch_scc1 .LBB0_10
	s_cmp_gt_u32 s43, 6
	s_cselect_b64 s[18:19], -1, 0
	s_and_b64 s[4:5], s[18:19], exec
	s_cselect_b32 s49, -7, 0
	s_add_i32 s49, s49, s43
	s_mov_b64 s[24:25], -1
	s_mov_b64 s[22:23], 0
	s_cmp_lt_i32 s49, 3
	s_mov_b64 s[20:21], 0
	s_cbranch_scc0 .LBB0_31
	s_movk_i32 s47, 0x800
	s_and_b64 vcc, exec, s[24:25]
	s_cbranch_vccnz .LBB0_43

; __device__ __forceinline__ unsigned cvt_pk_bf16(float lo, float hi) { unsigned r; asm volatile("v_cvt_pk_bf16_f32 %0, %1, %2" : "=v"(r) : "v"(lo), "v"(hi)); return r; }
; __device__ __forceinline__ void st16_wt(void* p, u32x4 v) { asm volatile("global_store_dwordx4 %0, %1, off sc1\n\ts_nop 1" :: "v"(p), "v"(v) : "memory"); }
; __device__ __forceinline__ void tr_item(const float* __restrict__ W, int K, int N, bf16_t* WT, const float* __restrict__ kscale, int rowmode, int item, int lane) {
;     const int nblk = N >> 5, kb = item / nblk, nb = item - kb * nblk;
;     const int c = lane >> 3, q = lane & 7, k0 = kb * 64 + c * 8, n0 = nb * 32 + q * 4;
;     f32x4 v[8];
; #pragma unroll
;     for (int i = 0; i < 8; ++i) v[i] = __builtin_nontemporal_load((const f32x4*)(W + (size_t)(k0 + i) * N + n0));
;     if (kscale) { const f32x4 s0 = *(const f32x4*)(kscale + k0), s1 = *(const f32x4*)(kscale + k0 + 4);
; #pragma unroll
;         for (int i = 0; i < 4; ++i) { v[i] = v[i] * s0[i]; v[4 + i] = v[4 + i] * s1[i]; } }
;     int drow;
;     if (rowmode == 0) drow = n0;
;     else if (rowmode == 3) { const int g = n0 - pg8::C_GA; drow = g < 0 ? n0 : pg8::C_GA + (((g & 2047) >> 7) << 8) + ((g >> 11) << 7) + (g & 127); }
;     else drow = ((n0 >> 7) << 8) + (n0 & 127) + (rowmode == 2 ? 128 : 0);
; #pragma unroll
;     for (int e = 0; e < 4; ++e) { u32x4 o; o.x = cvt_pk_bf16(v[0][e], v[1][e]); o.y = cvt_pk_bf16(v[2][e], v[3][e]); o.z = cvt_pk_bf16(v[4][e], v[5][e]); o.w = cvt_pk_bf16(v[6][e], v[7][e]);
;         pg8::st16_wt(WT + (size_t)(drow + e) * K + k0, o); }
; __device__ __forceinline__ void xcd_barrier(const XcdBarrier& b) {
;     ...
;     }
;     __syncthreads();
.LBB0_310:
	s_or_b64 exec, exec, s[6:7]
	s_cmp_lg_u32 s64, 0
	s_cbranch_scc1 .Lcv_skip_0
	v_readfirstlane_b32 vcc_lo, v204
	v_and_b32_e32 v106, 63, v204
	v_lshrrev_b32_e32 v107, 3, v106
	v_and_b32_e32 v108, 7, v106
	s_lshr_b32 vcc_lo, vcc_lo, 6
	s_cmp_eq_u32 vcc_lo, 0
	s_cbranch_scc1 .Lcv_skip_0
	s_mul_i32 vcc_hi, s85, 7
	s_add_i32 vcc_lo, vcc_lo, vcc_hi
	s_add_i32 vcc_lo, vcc_lo, -1
	s_cmp_ge_u32 vcc_lo, 7040
	s_cbranch_scc1 .Lcv_skip_0
	s_mov_b32 vcc_hi, 0
	s_mov_b32 m0, 0
	s_cmp_ge_u32 vcc_lo, 3520
	s_cbranch_scc0 .Lcv_l0_0
	s_sub_u32 vcc_lo, vcc_lo, 3520
	s_mov_b32 vcc_hi, 0x2c00000
	s_mov_b32 m0, 0x2000
.Lcv_l0_0:
	v_mov_b32_e32 v113, vcc_lo
	v_mul_u32_u24_e32 v109, 0x5d18, v113
	v_lshrrev_b32_e32 v109, 22, v109
	v_mul_u32_u24_e32 v110, 0xb0, v109
	v_sub_u32_e32 v110, v113, v110
	v_lshlrev_b32_e32 v109, 6, v109
	v_lshl_add_u32 v109, v107, 3, v109
	v_lshlrev_b32_e32 v110, 5, v110
	v_lshl_add_u32 v110, v108, 2, v110
	v_mul_u32_u24_e32 v111, 0x5800, v109
	v_lshl_add_u32 v111, v110, 2, v111
	v_add_u32_e32 v111, vcc_hi, v111
	v_lshrrev_b32_e32 v112, 7, v110
	v_lshlrev_b32_e32 v112, 8, v112
	v_and_b32_e32 v113, 0x7f, v110
	v_add_u32_e32 v112, v112, v113
	v_lshlrev_b32_e32 v112, 12, v112
	v_lshl_add_u32 v112, v109, 1, v112
	v_add_u32_e32 v112, vcc_hi, v112
	v_lshlrev_b32_e32 v113, 2, v109
	v_add_u32_e32 v113, m0, v113
	v_readlane_b32 vcc_lo, v250, 28
	v_readlane_b32 vcc_hi, v250, 29
	s_nop 4
	global_load_dwordx4 v[98:101], v113, vcc
	global_load_dwordx4 v[102:105], v113, vcc offset:16
	v_readlane_b32 vcc_lo, v250, 30
	v_readlane_b32 vcc_hi, v250, 31
	s_nop 4
	global_load_dwordx4 v[66:69], v111, vcc nt
	v_add_u32_e32 v111, 0x5800, v111
	global_load_dwordx4 v[70:73], v111, vcc nt
	v_add_u32_e32 v111, 0x5800, v111
	global_load_dwordx4 v[74:77], v111, vcc nt
	v_add_u32_e32 v111, 0x5800, v111
	global_load_dwordx4 v[78:81], v111, vcc nt
	v_add_u32_e32 v111, 0x5800, v111
	global_load_dwordx4 v[82:85], v111, vcc nt
	v_add_u32_e32 v111, 0x5800, v111
	global_load_dwordx4 v[86:89], v111, vcc nt
	v_add_u32_e32 v111, 0x5800, v111
	global_load_dwordx4 v[90:93], v111, vcc nt
	v_add_u32_e32 v111, 0x5800, v111
	global_load_dwordx4 v[94:97], v111, vcc nt
	v_readlane_b32 vcc_lo, v250, 36
	v_readlane_b32 vcc_hi, v250, 37
	s_nop 3
	s_add_u32 vcc_lo, vcc_lo, 0x5dc0000
	s_addc_u32 vcc_hi, vcc_hi, 0
	s_waitcnt vmcnt(0)
	v_mul_f32_e32 v66, v66, v98
	v_mul_f32_e32 v67, v67, v98
	v_mul_f32_e32 v68, v68, v98
	v_mul_f32_e32 v69, v69, v98
	v_mul_f32_e32 v70, v70, v99
	v_mul_f32_e32 v71, v71, v99
	v_mul_f32_e32 v72, v72, v99
	v_mul_f32_e32 v73, v73, v99
	v_mul_f32_e32 v74, v74, v100
	v_mul_f32_e32 v75, v75, v100
	v_mul_f32_e32 v76, v76, v100
	v_mul_f32_e32 v77, v77, v100
	v_mul_f32_e32 v78, v78, v101
	v_mul_f32_e32 v79, v79, v101
	v_mul_f32_e32 v80, v80, v101
	v_mul_f32_e32 v81, v81, v101
	v_mul_f32_e32 v82, v82, v102
	v_mul_f32_e32 v83, v83, v102
	v_mul_f32_e32 v84, v84, v102
	v_mul_f32_e32 v85, v85, v102
	v_mul_f32_e32 v86, v86, v103
	v_mul_f32_e32 v87, v87, v103
	v_mul_f32_e32 v88, v88, v103
	v_mul_f32_e32 v89, v89, v103
	v_mul_f32_e32 v90, v90, v104
	v_mul_f32_e32 v91, v91, v104
	v_mul_f32_e32 v92, v92, v104
	v_mul_f32_e32 v93, v93, v104
	v_mul_f32_e32 v94, v94, v105
	v_mul_f32_e32 v95, v95, v105
	v_mul_f32_e32 v96, v96, v105
	v_mul_f32_e32 v97, v97, v105
	v_cvt_pk_bf16_f32 v114, v66, v70
	v_cvt_pk_bf16_f32 v115, v74, v78
	v_cvt_pk_bf16_f32 v116, v82, v86
	v_cvt_pk_bf16_f32 v117, v90, v94
	v_cvt_pk_bf16_f32 v118, v67, v71
	v_cvt_pk_bf16_f32 v119, v75, v79
	v_cvt_pk_bf16_f32 v120, v83, v87
	v_cvt_pk_bf16_f32 v121, v91, v95
	v_cvt_pk_bf16_f32 v122, v68, v72
	v_cvt_pk_bf16_f32 v123, v76, v80
	v_cvt_pk_bf16_f32 v124, v84, v88
	v_cvt_pk_bf16_f32 v125, v92, v96
	v_cvt_pk_bf16_f32 v126, v69, v73
	v_cvt_pk_bf16_f32 v127, v77, v81
	v_cvt_pk_bf16_f32 v128, v85, v89
	v_cvt_pk_bf16_f32 v129, v93, v97
	global_store_dwordx4 v112, v[114:117], vcc sc1
	v_add_u32_e32 v112, 0x1000, v112
	global_store_dwordx4 v112, v[118:121], vcc sc1
	v_add_u32_e32 v112, 0x1000, v112
	global_store_dwordx4 v112, v[122:125], vcc sc1
	v_add_u32_e32 v112, 0x1000, v112
	global_store_dwordx4 v112, v[126:129], vcc sc1
.Lcv_skip_0:
	s_mov_b64 s[6:7], 0
	s_waitcnt lgkmcnt(0)
	s_barrier

;     ...
;         else if (kind == 4) { W = a.in[14] + (size_t)l * 2048 * 5632; K = 2048; N = 5632; WT = (bf16_t*)(ws + WS_WGU + l * SZ_WGU); ks = a.in[13] + l * 2048; rm = 1; }
;         else if (kind == 5) { W = a.in[15] + (size_t)l * 2048 * 5632; K = 2048; N = 5632; WT = (bf16_t*)(ws + WS_WGU + l * SZ_WGU); ks = a.in[13] + l * 2048; rm = 2; }
;         else                { W = a.in[16] + (size_t)l * 5632 * 2048; K = 5632; N = 2048; WT = (bf16_t*)(ws + WS_WD + l * SZ_WD); }
;         const int nitems = (K >> 6) * (N >> 5);
;         int ilo = 0, ihi = nitems; if ((fmask >> mi) & 1u) { ilo = (nitems * flo) >> 4; ihi = (nitems * fhi) >> 4; }
;         const int cnt = ihi - ilo;
;         int first = (gw - base) % NGW; if (first < 0) first += NGW;
;         for (int it = first; it < cnt; it += NGW) tr_item(W, K, N, WT, ks, rm, ilo + it, lane);
.LBB0_400:
	s_or_b64 exec, exec, s[0:1]
	s_cmp_lg_u32 s64, 0
	s_cbranch_scc1 .Lcv_skip_1
	v_readfirstlane_b32 vcc_lo, v204
	v_and_b32_e32 v106, 63, v204
	v_lshrrev_b32_e32 v107, 3, v106
	v_and_b32_e32 v108, 7, v106
	s_lshr_b32 vcc_lo, vcc_lo, 6
	s_cmp_eq_u32 vcc_lo, 0
	s_cbranch_scc1 .Lcv_skip_1
	s_mul_i32 vcc_hi, s85, 7
	s_add_i32 vcc_lo, vcc_lo, vcc_hi
	s_add_i32 vcc_lo, vcc_lo, 1791
	s_cmp_ge_u32 vcc_lo, 7040
	s_cbranch_scc1 .Lcv_skip_1
	s_mov_b32 vcc_hi, 0
	s_mov_b32 m0, 0
	s_cmp_ge_u32 vcc_lo, 3520
	s_cbranch_scc0 .Lcv_l0_1
	s_sub_u32 vcc_lo, vcc_lo, 3520
	s_mov_b32 vcc_hi, 0x2c00000
	s_mov_b32 m0, 0x2000

; __device__ __forceinline__ void xcd_barrier(const XcdBarrier& b) {
;     ...
;     __syncthreads();
.Lcv_skip_1:
	s_mov_b64 s[0:1], 0
	s_waitcnt lgkmcnt(0)
	s_barrier

;     ...
;         else if (kind == 4) { W = a.in[14] + (size_t)l * 2048 * 5632; K = 2048; N = 5632; WT = (bf16_t*)(ws + WS_WGU + l * SZ_WGU); ks = a.in[13] + l * 2048; rm = 1; }
;         else if (kind == 5) { W = a.in[15] + (size_t)l * 2048 * 5632; K = 2048; N = 5632; WT = (bf16_t*)(ws + WS_WGU + l * SZ_WGU); ks = a.in[13] + l * 2048; rm = 2; }
;         else                { W = a.in[16] + (size_t)l * 5632 * 2048; K = 5632; N = 2048; WT = (bf16_t*)(ws + WS_WD + l * SZ_WD); }
;         const int nitems = (K >> 6) * (N >> 5);
;         int ilo = 0, ihi = nitems; if ((fmask >> mi) & 1u) { ilo = (nitems * flo) >> 4; ihi = (nitems * fhi) >> 4; }
;         const int cnt = ihi - ilo;
;         int first = (gw - base) % NGW; if (first < 0) first += NGW;
;         for (int it = first; it < cnt; it += NGW) tr_item(W, K, N, WT, ks, rm, ilo + it, lane);
.LBB0_524:
	s_or_b64 exec, exec, s[0:1]
	s_cmp_lg_u32 s64, 0
	s_cbranch_scc1 .Lcv_skip_2
	v_readfirstlane_b32 vcc_lo, v204
	v_and_b32_e32 v106, 63, v204
	v_lshrrev_b32_e32 v107, 3, v106
	v_and_b32_e32 v108, 7, v106
	s_lshr_b32 vcc_lo, vcc_lo, 6
	s_cmp_eq_u32 vcc_lo, 0
	s_cbranch_scc1 .Lcv_skip_2
	s_mul_i32 vcc_hi, s85, 7
	s_add_i32 vcc_lo, vcc_lo, vcc_hi
	s_add_i32 vcc_lo, vcc_lo, 3583
	s_cmp_ge_u32 vcc_lo, 7040
	s_cbranch_scc1 .Lcv_skip_2
	s_mov_b32 vcc_hi, 0
	s_mov_b32 m0, 0
	s_cmp_ge_u32 vcc_lo, 3520
	s_cbranch_scc0 .Lcv_l0_2
	s_sub_u32 vcc_lo, vcc_lo, 3520
	s_mov_b32 vcc_hi, 0x2c00000
	s_mov_b32 m0, 0x2000

;     ...
;         else if (kind == 4) { W = a.in[14] + (size_t)l * 2048 * 5632; K = 2048; N = 5632; WT = (bf16_t*)(ws + WS_WGU + l * SZ_WGU); ks = a.in[13] + l * 2048; rm = 1; }
;         else if (kind == 5) { W = a.in[15] + (size_t)l * 2048 * 5632; K = 2048; N = 5632; WT = (bf16_t*)(ws + WS_WGU + l * SZ_WGU); ks = a.in[13] + l * 2048; rm = 2; }
;         else                { W = a.in[16] + (size_t)l * 5632 * 2048; K = 5632; N = 2048; WT = (bf16_t*)(ws + WS_WD + l * SZ_WD); }
;         const int nitems = (K >> 6) * (N >> 5);
;         int ilo = 0, ihi = nitems; if ((fmask >> mi) & 1u) { ilo = (nitems * flo) >> 4; ihi = (nitems * fhi) >> 4; }
;         const int cnt = ihi - ilo;
;         int first = (gw - base) % NGW; if (first < 0) first += NGW;
;         for (int it = first; it < cnt; it += NGW) tr_item(W, K, N, WT, ks, rm, ilo + it, lane);
.LBB0_632:
	s_or_b64 exec, exec, s[0:1]
	s_cmp_lg_u32 s64, 0
	s_cbranch_scc1 .Lcv_skip_3
	v_readfirstlane_b32 vcc_lo, v204
	v_and_b32_e32 v106, 63, v204
	v_lshrrev_b32_e32 v107, 3, v106
	v_and_b32_e32 v108, 7, v106
	s_lshr_b32 vcc_lo, vcc_lo, 6
	s_cmp_eq_u32 vcc_lo, 0
	s_cbranch_scc1 .Lcv_skip_3
	s_mul_i32 vcc_hi, s85, 7
	s_add_i32 vcc_lo, vcc_lo, vcc_hi
	s_add_i32 vcc_lo, vcc_lo, 5375
	s_cmp_ge_u32 vcc_lo, 7040
	s_cbranch_scc1 .Lcv_skip_3
	s_mov_b32 vcc_hi, 0
	s_mov_b32 m0, 0
	s_cmp_ge_u32 vcc_lo, 3520
	s_cbranch_scc0 .Lcv_l0_3
	s_sub_u32 vcc_lo, vcc_lo, 3520
	s_mov_b32 vcc_hi, 0x2c00000
	s_mov_b32 m0, 0x2000
